# Fourier in-proj tile loop: first fragment reads of the next K-slab issued right after the slab barrier, under the last four MFMAs (on top of v20)
# speedup vs baseline: 1.0019x; 1.0019x over previous
.LBB0_1512:
	s_ashr_i32 s1, s0, 31
	s_lshr_b32 s1, s1, 28
	s_add_i32 s1, s0, s1
	s_and_b32 s1, s1, 0xfffff0
	s_lshl_b32 s13, s4, 8
	s_sub_i32 s0, s0, s1
	v_add_u32_e32 v8, s13, v202
	s_lshl_b32 s12, s0, 8
	v_readlane_b32 s0, v254, 53
	v_add_u32_e32 v6, 64, v8
	v_add_u32_e32 v2, s12, v202
	v_and_b32_e32 v7, s0, v6
	v_ashrrev_i32_e32 v3, 31, v2
	v_lshrrev_b32_e32 v9, s51, v7
	v_and_b32_e32 v7, s52, v6
	v_lshlrev_b64 v[2:3], 11, v[2:3]
	v_and_b32_e32 v10, s14, v6
	v_lshlrev_b32_e32 v11, 7, v7
	s_waitcnt vmcnt(63) expcnt(7) lgkmcnt(15)
	s_barrier
	s_waitcnt vmcnt(7)
	ds_write_b128 v204, v[162:165]
	s_waitcnt vmcnt(6)
	ds_write_b128 v204, v[166:169] offset:9216
	s_waitcnt vmcnt(5)
	ds_write_b128 v204, v[170:173] offset:18432
	s_waitcnt vmcnt(4)
	ds_write_b128 v204, v[174:177] offset:27648
	s_waitcnt vmcnt(3)
	ds_write_b128 v204, v[178:181] offset:36864
	s_waitcnt vmcnt(2)
	ds_write_b128 v204, v[182:185] offset:46080
	s_waitcnt vmcnt(1)
	ds_write_b128 v204, v[186:189] offset:55296
	s_waitcnt vmcnt(0)
	ds_write_b128 v204, v[190:193] offset:64512
	v_and_b32_e32 v4, s0, v8
	v_and_b32_e32 v5, s14, v8
	v_add_u32_e32 v6, 0x80, v8
	v_add_u32_e32 v8, 0xc0, v8
	v_lshl_add_u64 v[162:163], v[198:199], 0, v[2:3]
	v_add3_u32 v2, v10, v9, v11
	v_and_b32_e32 v7, s0, v6
	v_and_b32_e32 v12, s0, v8
	v_and_b32_e32 v13, s52, v8
	v_ashrrev_i32_e32 v3, 31, v2
	v_lshrrev_b32_e32 v4, s51, v4
	v_lshrrev_b32_e32 v7, s51, v7
	v_and_b32_e32 v6, s14, v6
	v_lshrrev_b32_e32 v12, s51, v12
	v_and_b32_e32 v8, s14, v8
	v_lshlrev_b32_e32 v13, 7, v13
	v_lshlrev_b64 v[2:3], 11, v[2:3]
	v_add3_u32 v4, v5, v203, v4
	v_add3_u32 v6, v6, v203, v7
	v_lshl_add_u64 v[166:167], v[200:201], 0, v[2:3]
	v_add3_u32 v2, v8, v12, v13
	v_ashrrev_i32_e32 v5, 31, v4
	v_ashrrev_i32_e32 v7, 31, v6
	v_ashrrev_i32_e32 v3, 31, v2
	v_lshlrev_b64 v[4:5], 11, v[4:5]
	v_lshlrev_b64 v[6:7], 11, v[6:7]
	v_lshlrev_b64 v[2:3], 11, v[2:3]
	v_mov_b32_e32 v98, 0
	v_lshl_add_u64 v[164:165], v[200:201], 0, v[4:5]
	v_lshl_add_u64 v[168:169], v[200:201], 0, v[6:7]
	v_lshl_add_u64 v[170:171], v[200:201], 0, v[2:3]
	s_mov_b32 s10, 0
	s_mov_b64 s[0:1], 0
	v_mov_b32_e32 v99, v98
	v_mov_b32_e32 v100, v98
	v_mov_b32_e32 v101, v98
	v_mov_b32_e32 v102, v98
	v_mov_b32_e32 v103, v98
	v_mov_b32_e32 v104, v98
	v_mov_b32_e32 v105, v98
	v_mov_b32_e32 v106, v98
	v_mov_b32_e32 v107, v98
	v_mov_b32_e32 v108, v98
	v_mov_b32_e32 v109, v98
	v_mov_b32_e32 v110, v98
	v_mov_b32_e32 v111, v98
	v_mov_b32_e32 v112, v98
	v_mov_b32_e32 v113, v98
	v_mov_b32_e32 v66, v98
	v_mov_b32_e32 v67, v98
	v_mov_b32_e32 v68, v98
	v_mov_b32_e32 v69, v98
	v_mov_b32_e32 v70, v98
	v_mov_b32_e32 v71, v98
	v_mov_b32_e32 v72, v98
	v_mov_b32_e32 v73, v98
	v_mov_b32_e32 v74, v98
	v_mov_b32_e32 v75, v98
	v_mov_b32_e32 v76, v98
	v_mov_b32_e32 v77, v98
	v_mov_b32_e32 v78, v98
	v_mov_b32_e32 v79, v98
	v_mov_b32_e32 v80, v98
	v_mov_b32_e32 v81, v98
	v_mov_b32_e32 v34, v98
	v_mov_b32_e32 v35, v98
	v_mov_b32_e32 v36, v98
	v_mov_b32_e32 v37, v98
	v_mov_b32_e32 v38, v98
	v_mov_b32_e32 v39, v98
	v_mov_b32_e32 v40, v98
	v_mov_b32_e32 v41, v98
	v_mov_b32_e32 v42, v98
	v_mov_b32_e32 v43, v98
	v_mov_b32_e32 v44, v98
	v_mov_b32_e32 v45, v98
	v_mov_b32_e32 v46, v98
	v_mov_b32_e32 v47, v98
	v_mov_b32_e32 v48, v98
	v_mov_b32_e32 v49, v98
	v_mov_b32_e32 v2, v98
	v_mov_b32_e32 v3, v98
	v_mov_b32_e32 v4, v98
	v_mov_b32_e32 v5, v98
	v_mov_b32_e32 v6, v98
	v_mov_b32_e32 v7, v98
	v_mov_b32_e32 v8, v98
	v_mov_b32_e32 v9, v98
	v_mov_b32_e32 v10, v98
	v_mov_b32_e32 v11, v98
	v_mov_b32_e32 v12, v98
	v_mov_b32_e32 v13, v98
	v_mov_b32_e32 v14, v98
	v_mov_b32_e32 v15, v98
	v_mov_b32_e32 v16, v98
	v_mov_b32_e32 v17, v98
	v_mov_b32_e32 v114, v98
	v_mov_b32_e32 v115, v98
	v_mov_b32_e32 v116, v98
	v_mov_b32_e32 v117, v98
	v_mov_b32_e32 v118, v98
	v_mov_b32_e32 v119, v98
	v_mov_b32_e32 v120, v98
	v_mov_b32_e32 v121, v98
	v_mov_b32_e32 v122, v98
	v_mov_b32_e32 v123, v98
	v_mov_b32_e32 v124, v98
	v_mov_b32_e32 v125, v98
	v_mov_b32_e32 v126, v98
	v_mov_b32_e32 v127, v98
	v_mov_b32_e32 v128, v98
	v_mov_b32_e32 v129, v98
	v_mov_b32_e32 v82, v98
	v_mov_b32_e32 v83, v98
	v_mov_b32_e32 v84, v98
	v_mov_b32_e32 v85, v98
	v_mov_b32_e32 v86, v98
	v_mov_b32_e32 v87, v98
	v_mov_b32_e32 v88, v98
	v_mov_b32_e32 v89, v98
	v_mov_b32_e32 v90, v98
	v_mov_b32_e32 v91, v98
	v_mov_b32_e32 v92, v98
	v_mov_b32_e32 v93, v98
	v_mov_b32_e32 v94, v98
	v_mov_b32_e32 v95, v98
	v_mov_b32_e32 v96, v98
	v_mov_b32_e32 v97, v98
	v_mov_b32_e32 v50, v98
	v_mov_b32_e32 v51, v98
	v_mov_b32_e32 v52, v98
	v_mov_b32_e32 v53, v98
	v_mov_b32_e32 v54, v98
	v_mov_b32_e32 v55, v98
	v_mov_b32_e32 v56, v98
	v_mov_b32_e32 v57, v98
	v_mov_b32_e32 v58, v98
	v_mov_b32_e32 v59, v98
	v_mov_b32_e32 v60, v98
	v_mov_b32_e32 v61, v98
	v_mov_b32_e32 v62, v98
	v_mov_b32_e32 v63, v98
	v_mov_b32_e32 v64, v98
	v_mov_b32_e32 v65, v98
	v_mov_b32_e32 v18, v98
	v_mov_b32_e32 v19, v98
	v_mov_b32_e32 v20, v98
	v_mov_b32_e32 v21, v98
	v_mov_b32_e32 v22, v98
	v_mov_b32_e32 v23, v98
	v_mov_b32_e32 v24, v98
	v_mov_b32_e32 v25, v98
	v_mov_b32_e32 v26, v98
	v_mov_b32_e32 v27, v98
	v_mov_b32_e32 v28, v98
	v_mov_b32_e32 v29, v98
	v_mov_b32_e32 v30, v98
	v_mov_b32_e32 v31, v98
	v_mov_b32_e32 v32, v98
	v_mov_b32_e32 v33, v98
	s_waitcnt lgkmcnt(0)
	s_barrier
	s_and_b32 s11, s10, 1
	s_mul_i32 s15, s11, 0x12000
	v_add_u32_e32 v172, s15, v226
	v_add3_u32 v172, v172, v228, v229
	v_add_u32_e32 v173, s15, v227
	v_add3_u32 v173, v173, v228, v229
	ds_read_b128 v[174:177], v172
	ds_read_b128 v[178:181], v173 offset:36864
	ds_read_b128 v[182:185], v173 offset:41472
	ds_read_b128 v[186:189], v173 offset:46080
	ds_read_b128 v[190:193], v173 offset:50688
	ds_read_b128 v[248:251], v172 offset:4608
	s_branch .LBB0_1514
.LBB0_1514:
	s_cmpk_lg_i32 s0, 0x780
	s_cselect_b64 s[4:5], -1, 0
	s_cmpk_eq_i32 s0, 0x780
	s_cbranch_scc1 .Lyp_last
	s_waitcnt vmcnt(5)
	v_lshl_add_u64 v[138:139], v[162:163], 0, s[0:1]
	v_add_co_u32_e32 v130, vcc, 0x2a00000, v138
	s_waitcnt vmcnt(3)
	v_lshl_add_u64 v[146:147], v[164:165], 0, s[0:1]
	v_addc_co_u32_e32 v131, vcc, 0, v139, vcc
	v_add_co_u32_e32 v134, vcc, 0x2a20000, v138
	s_waitcnt vmcnt(2)
	v_lshl_add_u64 v[150:151], v[166:167], 0, s[0:1]
	v_addc_co_u32_e32 v135, vcc, 0, v139, vcc
	v_add_co_u32_e32 v140, vcc, 0x2a40000, v138
	s_waitcnt vmcnt(1)
	v_lshl_add_u64 v[154:155], v[168:169], 0, s[0:1]
	v_addc_co_u32_e32 v141, vcc, 0, v139, vcc
	v_add_co_u32_e32 v142, vcc, 0x2a60000, v138
	s_waitcnt vmcnt(0)
	v_lshl_add_u64 v[158:159], v[170:171], 0, s[0:1]
	v_addc_co_u32_e32 v143, vcc, 0, v139, vcc
	global_load_dwordx4 v[130:133], v[130:131], off offset:128
	s_nop 0
	global_load_dwordx4 v[134:137], v[134:135], off offset:128
	s_nop 0
	global_load_dwordx4 v[138:141], v[140:141], off offset:128
	s_nop 0
	global_load_dwordx4 v[142:145], v[142:143], off offset:128
	s_nop 0
	global_load_dwordx4 v[146:149], v[146:147], off
	s_nop 0
	global_load_dwordx4 v[150:153], v[150:151], off
	s_nop 0
	global_load_dwordx4 v[154:157], v[154:155], off
	s_nop 0
	global_load_dwordx4 v[158:161], v[158:159], off
	s_xor_b32 s4, s11, 1
	s_mul_i32 s4, s4, 0x12000
	v_add_u32_e32 v218, s4, v204
	s_add_u32 s0, s0, 0x80
	s_addc_u32 s1, s1, 0
	s_add_i32 s10, s10, 1
	s_waitcnt lgkmcnt(4)
	v_mfma_f32_32x32x16_bf16 v[98:113], v[174:177], v[178:181], v[98:113]
	s_waitcnt lgkmcnt(3)
	v_mfma_f32_32x32x16_bf16 v[66:81], v[174:177], v[182:185], v[66:81]
	s_waitcnt lgkmcnt(2)
	v_mfma_f32_32x32x16_bf16 v[34:49], v[174:177], v[186:189], v[34:49]
	s_waitcnt lgkmcnt(1)
	v_mfma_f32_32x32x16_bf16 v[2:17], v[174:177], v[190:193], v[2:17]
	ds_read_b128 v[214:217], v172 offset:32
	ds_read_b128 v[232:235], v173 offset:36896
	ds_read_b128 v[236:239], v173 offset:41504
	ds_read_b128 v[240:243], v173 offset:46112
	ds_read_b128 v[244:247], v173 offset:50720
	s_waitcnt lgkmcnt(5)
	v_mfma_f32_32x32x16_bf16 v[114:129], v[248:251], v[178:181], v[114:129]
	v_mfma_f32_32x32x16_bf16 v[82:97], v[248:251], v[182:185], v[82:97]
	v_mfma_f32_32x32x16_bf16 v[50:65], v[248:251], v[186:189], v[50:65]
	v_mfma_f32_32x32x16_bf16 v[18:33], v[248:251], v[190:193], v[18:33]
	ds_read_b128 v[248:251], v172 offset:4640
	s_waitcnt vmcnt(7)
	ds_write_b128 v218, v[130:133]
	s_waitcnt lgkmcnt(5)
	v_mfma_f32_32x32x16_bf16 v[98:113], v[214:217], v[232:235], v[98:113]
	s_waitcnt lgkmcnt(4)
	v_mfma_f32_32x32x16_bf16 v[66:81], v[214:217], v[236:239], v[66:81]
	s_waitcnt lgkmcnt(3)
	v_mfma_f32_32x32x16_bf16 v[34:49], v[214:217], v[240:243], v[34:49]
	s_waitcnt lgkmcnt(2)
	v_mfma_f32_32x32x16_bf16 v[2:17], v[214:217], v[244:247], v[2:17]
	ds_read_b128 v[174:177], v172 offset:64
	ds_read_b128 v[178:181], v173 offset:36928
	ds_read_b128 v[182:185], v173 offset:41536
	ds_read_b128 v[186:189], v173 offset:46144
	ds_read_b128 v[190:193], v173 offset:50752
	s_waitcnt vmcnt(6)
	ds_write_b128 v218, v[134:137] offset:9216
	s_waitcnt lgkmcnt(7)
	v_mfma_f32_32x32x16_bf16 v[114:129], v[248:251], v[232:235], v[114:129]
	v_mfma_f32_32x32x16_bf16 v[82:97], v[248:251], v[236:239], v[82:97]
	v_mfma_f32_32x32x16_bf16 v[50:65], v[248:251], v[240:243], v[50:65]
	v_mfma_f32_32x32x16_bf16 v[18:33], v[248:251], v[244:247], v[18:33]
	ds_read_b128 v[248:251], v172 offset:4672
	s_waitcnt vmcnt(5)
	ds_write_b128 v218, v[138:141] offset:18432
	s_waitcnt vmcnt(4)
	ds_write_b128 v218, v[142:145] offset:27648
	s_waitcnt lgkmcnt(7)
	v_mfma_f32_32x32x16_bf16 v[98:113], v[174:177], v[178:181], v[98:113]
	s_waitcnt lgkmcnt(6)
	v_mfma_f32_32x32x16_bf16 v[66:81], v[174:177], v[182:185], v[66:81]
	s_waitcnt lgkmcnt(5)
	v_mfma_f32_32x32x16_bf16 v[34:49], v[174:177], v[186:189], v[34:49]
	s_waitcnt lgkmcnt(4)
	v_mfma_f32_32x32x16_bf16 v[2:17], v[174:177], v[190:193], v[2:17]
	ds_read_b128 v[214:217], v172 offset:96
	ds_read_b128 v[232:235], v173 offset:36960
	ds_read_b128 v[236:239], v173 offset:41568
	ds_read_b128 v[240:243], v173 offset:46176
	ds_read_b128 v[244:247], v173 offset:50784
	s_waitcnt vmcnt(3)
	ds_write_b128 v218, v[146:149] offset:36864
	s_waitcnt vmcnt(2)
	ds_write_b128 v218, v[150:153] offset:46080
	s_waitcnt lgkmcnt(9)
	v_mfma_f32_32x32x16_bf16 v[114:129], v[248:251], v[178:181], v[114:129]
	v_mfma_f32_32x32x16_bf16 v[82:97], v[248:251], v[182:185], v[82:97]
	v_mfma_f32_32x32x16_bf16 v[50:65], v[248:251], v[186:189], v[50:65]
	v_mfma_f32_32x32x16_bf16 v[18:33], v[248:251], v[190:193], v[18:33]
	ds_read_b128 v[248:251], v172 offset:4704
	s_waitcnt vmcnt(1)
	ds_write_b128 v218, v[154:157] offset:55296
	s_waitcnt vmcnt(0)
	ds_write_b128 v218, v[158:161] offset:64512
	s_waitcnt lgkmcnt(8)
	v_mfma_f32_32x32x16_bf16 v[98:113], v[214:217], v[232:235], v[98:113]
	s_waitcnt lgkmcnt(7)
	v_mfma_f32_32x32x16_bf16 v[66:81], v[214:217], v[236:239], v[66:81]
	s_waitcnt lgkmcnt(6)
	v_mfma_f32_32x32x16_bf16 v[34:49], v[214:217], v[240:243], v[34:49]
	s_waitcnt lgkmcnt(5)
	v_mfma_f32_32x32x16_bf16 v[2:17], v[214:217], v[244:247], v[2:17]
	s_and_b32 s11, s10, 1
	s_mul_i32 s15, s11, 0x12000
	v_add_u32_e32 v172, s15, v226
	v_add3_u32 v172, v172, v228, v229
	v_add_u32_e32 v173, s15, v227
	v_add3_u32 v173, v173, v228, v229
	s_waitcnt lgkmcnt(0)
	s_barrier
	ds_read_b128 v[174:177], v172
	ds_read_b128 v[178:181], v173 offset:36864
	ds_read_b128 v[182:185], v173 offset:41472
	ds_read_b128 v[186:189], v173 offset:46080
	ds_read_b128 v[190:193], v173 offset:50688
	v_mfma_f32_32x32x16_bf16 v[114:129], v[248:251], v[232:235], v[114:129]
	v_mfma_f32_32x32x16_bf16 v[82:97], v[248:251], v[236:239], v[82:97]
	v_mfma_f32_32x32x16_bf16 v[50:65], v[248:251], v[240:243], v[50:65]
	v_mfma_f32_32x32x16_bf16 v[18:33], v[248:251], v[244:247], v[18:33]
	ds_read_b128 v[248:251], v172 offset:4608
	s_branch .LBB0_1514
.Lyp_last:
	s_add_u32 s0, s0, 0x80
	s_addc_u32 s1, s1, 0
	s_add_i32 s10, s10, 1
	s_waitcnt lgkmcnt(4)
	v_mfma_f32_32x32x16_bf16 v[98:113], v[174:177], v[178:181], v[98:113]
	s_waitcnt lgkmcnt(3)
	v_mfma_f32_32x32x16_bf16 v[66:81], v[174:177], v[182:185], v[66:81]
	s_waitcnt lgkmcnt(2)
	v_mfma_f32_32x32x16_bf16 v[34:49], v[174:177], v[186:189], v[34:49]
	s_waitcnt lgkmcnt(1)
	v_mfma_f32_32x32x16_bf16 v[2:17], v[174:177], v[190:193], v[2:17]
	ds_read_b128 v[214:217], v172 offset:32
	ds_read_b128 v[232:235], v173 offset:36896
	ds_read_b128 v[236:239], v173 offset:41504
	ds_read_b128 v[240:243], v173 offset:46112
	ds_read_b128 v[244:247], v173 offset:50720
	s_waitcnt lgkmcnt(5)
	v_mfma_f32_32x32x16_bf16 v[114:129], v[248:251], v[178:181], v[114:129]
	v_mfma_f32_32x32x16_bf16 v[82:97], v[248:251], v[182:185], v[82:97]
	v_mfma_f32_32x32x16_bf16 v[50:65], v[248:251], v[186:189], v[50:65]
	v_mfma_f32_32x32x16_bf16 v[18:33], v[248:251], v[190:193], v[18:33]
	ds_read_b128 v[248:251], v172 offset:4640
	s_waitcnt lgkmcnt(4)
	v_mfma_f32_32x32x16_bf16 v[98:113], v[214:217], v[232:235], v[98:113]
	s_waitcnt lgkmcnt(3)
	v_mfma_f32_32x32x16_bf16 v[66:81], v[214:217], v[236:239], v[66:81]
	s_waitcnt lgkmcnt(2)
	v_mfma_f32_32x32x16_bf16 v[34:49], v[214:217], v[240:243], v[34:49]
	s_waitcnt lgkmcnt(1)
	v_mfma_f32_32x32x16_bf16 v[2:17], v[214:217], v[244:247], v[2:17]
	ds_read_b128 v[174:177], v172 offset:64
	ds_read_b128 v[178:181], v173 offset:36928
	ds_read_b128 v[182:185], v173 offset:41536
	ds_read_b128 v[186:189], v173 offset:46144
	ds_read_b128 v[190:193], v173 offset:50752
	s_waitcnt lgkmcnt(5)
	v_mfma_f32_32x32x16_bf16 v[114:129], v[248:251], v[232:235], v[114:129]
	v_mfma_f32_32x32x16_bf16 v[82:97], v[248:251], v[236:239], v[82:97]
	v_mfma_f32_32x32x16_bf16 v[50:65], v[248:251], v[240:243], v[50:65]
	v_mfma_f32_32x32x16_bf16 v[18:33], v[248:251], v[244:247], v[18:33]
	ds_read_b128 v[248:251], v172 offset:4672
	s_waitcnt lgkmcnt(4)
	v_mfma_f32_32x32x16_bf16 v[98:113], v[174:177], v[178:181], v[98:113]
	s_waitcnt lgkmcnt(3)
	v_mfma_f32_32x32x16_bf16 v[66:81], v[174:177], v[182:185], v[66:81]
	s_waitcnt lgkmcnt(2)
	v_mfma_f32_32x32x16_bf16 v[34:49], v[174:177], v[186:189], v[34:49]
	s_waitcnt lgkmcnt(1)
	v_mfma_f32_32x32x16_bf16 v[2:17], v[174:177], v[190:193], v[2:17]
	ds_read_b128 v[214:217], v172 offset:96
	ds_read_b128 v[232:235], v173 offset:36960
	ds_read_b128 v[236:239], v173 offset:41568
	ds_read_b128 v[240:243], v173 offset:46176
	ds_read_b128 v[244:247], v173 offset:50784
	s_waitcnt lgkmcnt(5)
	v_mfma_f32_32x32x16_bf16 v[114:129], v[248:251], v[178:181], v[114:129]
	v_mfma_f32_32x32x16_bf16 v[82:97], v[248:251], v[182:185], v[82:97]
	v_mfma_f32_32x32x16_bf16 v[50:65], v[248:251], v[186:189], v[50:65]
	v_mfma_f32_32x32x16_bf16 v[18:33], v[248:251], v[190:193], v[18:33]
	ds_read_b128 v[248:251], v172 offset:4704
	s_waitcnt lgkmcnt(4)
	v_mfma_f32_32x32x16_bf16 v[98:113], v[214:217], v[232:235], v[98:113]
	s_waitcnt lgkmcnt(3)
	v_mfma_f32_32x32x16_bf16 v[66:81], v[214:217], v[236:239], v[66:81]
	s_waitcnt lgkmcnt(2)
	v_mfma_f32_32x32x16_bf16 v[34:49], v[214:217], v[240:243], v[34:49]
	s_waitcnt lgkmcnt(1)
	v_mfma_f32_32x32x16_bf16 v[2:17], v[214:217], v[244:247], v[2:17]
	s_waitcnt lgkmcnt(0)
	s_barrier
	v_mfma_f32_32x32x16_bf16 v[114:129], v[248:251], v[232:235], v[114:129]
	v_mfma_f32_32x32x16_bf16 v[82:97], v[248:251], v[236:239], v[82:97]
	v_mfma_f32_32x32x16_bf16 v[50:65], v[248:251], v[240:243], v[50:65]
	v_mfma_f32_32x32x16_bf16 v[18:33], v[248:251], v[244:247], v[18:33]
